# v59 + GEMM1 K-loop: LDS-DMA loads in SGPR-base form and issued at the head of each load segment (before the fragment ds_reads)
# speedup vs baseline: 1.0084x; 1.0054x over previous
.LBB0_163:
	s_add_u32 s33, s52, 0xfffc0080
	s_addc_u32 s54, s53, -1
	s_cmp_eq_u32 s92, 12
	s_cselect_b32 s57, s18, s54
	s_cselect_b32 s56, s19, s33
	s_cselect_b32 s55, s17, s91
	s_cselect_b32 s54, s21, s90
	s_add_i32 m0, s26, 0xc000
	s_nop 0
	global_load_lds_dwordx4 v142, s[52:53]
	s_add_i32 m0, s26, 0xe000
	s_nop 0
	global_load_lds_dwordx4 v144, s[52:53]
	ds_read_b128 v[152:155], v163
	ds_read_b128 v[166:169], v163 offset:1024
	ds_read_b128 v[170:173], v163 offset:2048
	ds_read_b128 v[174:177], v163 offset:3072
	ds_read_b128 v[178:181], v164
	ds_read_b128 v[182:185], v164 offset:1024
	ds_read_b128 v[186:189], v164 offset:2048
	ds_read_b128 v[190:193], v164 offset:3072
	ds_read_b128 v[194:197], v165
	ds_read_b128 v[198:201], v165 offset:1024
	ds_read_b128 v[202:205], v165 offset:2048
	ds_read_b128 v[206:209], v165 offset:3072
	ds_read_b128 v[210:213], v165 offset:4096
	ds_read_b128 v[214:217], v165 offset:5120
	ds_read_b128 v[218:221], v165 offset:6144
	ds_read_b128 v[222:225], v165 offset:7168
	s_waitcnt vmcnt(8)
	s_waitcnt lgkmcnt(0)
	s_barrier
	s_setprio 1
	s_waitcnt lgkmcnt(0)
	v_mfma_f32_16x16x32_bf16 v[126:129], v[152:155], v[194:197], v[126:129]
	v_mfma_f32_16x16x32_bf16 v[122:125], v[170:173], v[194:197], v[122:125]
	v_mfma_f32_16x16x32_bf16 v[118:121], v[152:155], v[202:205], v[118:121]
	v_mfma_f32_16x16x32_bf16 v[114:117], v[170:173], v[202:205], v[114:117]
	v_mfma_f32_16x16x32_bf16 v[102:105], v[152:155], v[210:213], v[102:105]
	v_mfma_f32_16x16x32_bf16 v[98:101], v[170:173], v[210:213], v[98:101]
	v_mfma_f32_16x16x32_bf16 v[86:89], v[152:155], v[218:221], v[86:89]
	v_mfma_f32_16x16x32_bf16 v[82:85], v[170:173], v[218:221], v[82:85]
	v_mfma_f32_16x16x32_bf16 v[126:129], v[166:169], v[198:201], v[126:129]
	v_mfma_f32_16x16x32_bf16 v[122:125], v[174:177], v[198:201], v[122:125]
	v_mfma_f32_16x16x32_bf16 v[118:121], v[166:169], v[206:209], v[118:121]
	v_mfma_f32_16x16x32_bf16 v[114:117], v[174:177], v[206:209], v[114:117]
	v_mfma_f32_16x16x32_bf16 v[102:105], v[166:169], v[214:217], v[102:105]
	v_mfma_f32_16x16x32_bf16 v[98:101], v[174:177], v[214:217], v[98:101]
	v_mfma_f32_16x16x32_bf16 v[86:89], v[166:169], v[222:225], v[86:89]
	v_mfma_f32_16x16x32_bf16 v[82:85], v[174:177], v[222:225], v[82:85]
	s_setprio 0
	s_setprio 1
	v_mfma_f32_16x16x32_bf16 v[110:113], v[178:181], v[194:197], v[110:113]
	v_mfma_f32_16x16x32_bf16 v[106:109], v[186:189], v[194:197], v[106:109]
	v_mfma_f32_16x16x32_bf16 v[94:97], v[178:181], v[202:205], v[94:97]
	v_mfma_f32_16x16x32_bf16 v[90:93], v[186:189], v[202:205], v[90:93]
	v_mfma_f32_16x16x32_bf16 v[78:81], v[178:181], v[210:213], v[78:81]
	v_mfma_f32_16x16x32_bf16 v[74:77], v[186:189], v[210:213], v[74:77]
	v_mfma_f32_16x16x32_bf16 v[70:73], v[178:181], v[218:221], v[70:73]
	v_mfma_f32_16x16x32_bf16 v[66:69], v[186:189], v[218:221], v[66:69]
	v_mfma_f32_16x16x32_bf16 v[110:113], v[182:185], v[198:201], v[110:113]
	v_mfma_f32_16x16x32_bf16 v[106:109], v[190:193], v[198:201], v[106:109]
	v_mfma_f32_16x16x32_bf16 v[94:97], v[182:185], v[206:209], v[94:97]
	v_mfma_f32_16x16x32_bf16 v[90:93], v[190:193], v[206:209], v[90:93]
	v_mfma_f32_16x16x32_bf16 v[78:81], v[182:185], v[214:217], v[78:81]
	v_mfma_f32_16x16x32_bf16 v[74:77], v[190:193], v[214:217], v[74:77]
	v_mfma_f32_16x16x32_bf16 v[70:73], v[182:185], v[222:225], v[70:73]
	v_mfma_f32_16x16x32_bf16 v[66:69], v[190:193], v[222:225], v[66:69]
	s_setprio 0
	s_barrier
	s_add_i32 s33, s82, s25
	s_mov_b32 m0, s33
	s_nop 0
	global_load_lds_dwordx4 v134, s[54:55]
	s_add_i32 m0, s33, 0x2000
	s_add_u32 s94, s54, 0x40000
	s_addc_u32 s95, s55, 0
	s_add_i32 s33, s83, s25
	global_load_lds_dwordx4 v130, s[54:55]
	s_mov_b32 m0, s33
	s_add_u32 s100, s56, 0x80
	s_addc_u32 s101, s57, 0
	global_load_lds_dwordx4 v134, s[94:95]
	s_add_i32 m0, s33, 0x2000
	s_nop 0
	global_load_lds_dwordx4 v130, s[94:95]
	s_mov_b32 m0, s26
	s_nop 0
	global_load_lds_dwordx4 v136, s[56:57]
	s_mov_b32 m0, s27
	s_nop 0
	global_load_lds_dwordx4 v132, s[56:57]
	ds_read_b128 v[194:197], v165 offset:16384
	ds_read_b128 v[198:201], v165 offset:17408
	ds_read_b128 v[202:205], v165 offset:18432
	ds_read_b128 v[206:209], v165 offset:19456
	ds_read_b128 v[210:213], v165 offset:20480
	ds_read_b128 v[214:217], v165 offset:21504
	ds_read_b128 v[218:221], v165 offset:22528
	ds_read_b128 v[222:225], v165 offset:23552
	s_waitcnt vmcnt(8)
	s_waitcnt lgkmcnt(0)
	s_barrier
	s_setprio 1
	s_waitcnt lgkmcnt(0)
	v_mfma_f32_16x16x32_bf16 v[62:65], v[152:155], v[194:197], v[62:65]
	v_mfma_f32_16x16x32_bf16 v[58:61], v[170:173], v[194:197], v[58:61]
	v_mfma_f32_16x16x32_bf16 v[54:57], v[152:155], v[202:205], v[54:57]
	v_mfma_f32_16x16x32_bf16 v[50:53], v[170:173], v[202:205], v[50:53]
	v_mfma_f32_16x16x32_bf16 v[38:41], v[152:155], v[210:213], v[38:41]
	v_mfma_f32_16x16x32_bf16 v[34:37], v[170:173], v[210:213], v[34:37]
	v_mfma_f32_16x16x32_bf16 v[22:25], v[152:155], v[218:221], v[22:25]
	v_mfma_f32_16x16x32_bf16 v[18:21], v[170:173], v[218:221], v[18:21]
	v_mfma_f32_16x16x32_bf16 v[62:65], v[166:169], v[198:201], v[62:65]
	v_mfma_f32_16x16x32_bf16 v[58:61], v[174:177], v[198:201], v[58:61]
	v_mfma_f32_16x16x32_bf16 v[54:57], v[166:169], v[206:209], v[54:57]
	v_mfma_f32_16x16x32_bf16 v[50:53], v[174:177], v[206:209], v[50:53]
	v_mfma_f32_16x16x32_bf16 v[38:41], v[166:169], v[214:217], v[38:41]
	v_mfma_f32_16x16x32_bf16 v[34:37], v[174:177], v[214:217], v[34:37]
	v_mfma_f32_16x16x32_bf16 v[22:25], v[166:169], v[222:225], v[22:25]
	v_mfma_f32_16x16x32_bf16 v[18:21], v[174:177], v[222:225], v[18:21]
	s_setprio 0
	s_setprio 1
	v_mfma_f32_16x16x32_bf16 v[46:49], v[178:181], v[194:197], v[46:49]
	v_mfma_f32_16x16x32_bf16 v[42:45], v[186:189], v[194:197], v[42:45]
	v_mfma_f32_16x16x32_bf16 v[30:33], v[178:181], v[202:205], v[30:33]
	v_mfma_f32_16x16x32_bf16 v[26:29], v[186:189], v[202:205], v[26:29]
	v_mfma_f32_16x16x32_bf16 v[14:17], v[178:181], v[210:213], v[14:17]
	v_mfma_f32_16x16x32_bf16 v[10:13], v[186:189], v[210:213], v[10:13]
	v_mfma_f32_16x16x32_bf16 v[6:9], v[178:181], v[218:221], v[6:9]
	v_mfma_f32_16x16x32_bf16 v[2:5], v[186:189], v[218:221], v[2:5]
	v_mfma_f32_16x16x32_bf16 v[46:49], v[182:185], v[198:201], v[46:49]
	v_mfma_f32_16x16x32_bf16 v[42:45], v[190:193], v[198:201], v[42:45]
	v_mfma_f32_16x16x32_bf16 v[30:33], v[182:185], v[206:209], v[30:33]
	v_mfma_f32_16x16x32_bf16 v[26:29], v[190:193], v[206:209], v[26:29]
	v_mfma_f32_16x16x32_bf16 v[14:17], v[182:185], v[214:217], v[14:17]
	v_mfma_f32_16x16x32_bf16 v[10:13], v[190:193], v[214:217], v[10:13]
	v_mfma_f32_16x16x32_bf16 v[6:9], v[182:185], v[222:225], v[6:9]
	v_mfma_f32_16x16x32_bf16 v[2:5], v[190:193], v[222:225], v[2:5]
	s_setprio 0
	s_barrier
	s_add_i32 s33, 0, 0x18000
	s_add_i32 s80, 0, 0x1c000
	s_add_u32 s56, s56, 0x40000
	s_addc_u32 s57, s57, 0
	s_mov_b32 m0, s58
	s_nop 0
	global_load_lds_dwordx4 v136, s[56:57]
	s_mov_b32 m0, s59
	s_nop 0
	global_load_lds_dwordx4 v132, s[56:57]
	v_add_u32_e32 v138, s33, v158
	ds_read_b128 v[152:155], v138
	ds_read_b128 v[166:169], v138 offset:1024
	ds_read_b128 v[170:173], v138 offset:2048
	ds_read_b128 v[174:177], v138 offset:3072
	v_add_u32_e32 v138, s80, v158
	ds_read_b128 v[178:181], v138
	ds_read_b128 v[182:185], v138 offset:1024
	ds_read_b128 v[186:189], v138 offset:2048
	ds_read_b128 v[190:193], v138 offset:3072
	ds_read_b128 v[194:197], v165 offset:32768
	ds_read_b128 v[198:201], v165 offset:33792
	ds_read_b128 v[202:205], v165 offset:34816
	ds_read_b128 v[206:209], v165 offset:35840
	ds_read_b128 v[210:213], v165 offset:36864
	ds_read_b128 v[214:217], v165 offset:37888
	ds_read_b128 v[218:221], v165 offset:38912
	ds_read_b128 v[222:225], v165 offset:39936
	s_waitcnt vmcnt(8)
	s_waitcnt lgkmcnt(0)
	s_barrier
	s_setprio 1
	s_waitcnt lgkmcnt(0)
	v_mfma_f32_16x16x32_bf16 v[126:129], v[152:155], v[194:197], v[126:129]
	v_mfma_f32_16x16x32_bf16 v[122:125], v[170:173], v[194:197], v[122:125]
	v_mfma_f32_16x16x32_bf16 v[118:121], v[152:155], v[202:205], v[118:121]
	v_mfma_f32_16x16x32_bf16 v[114:117], v[170:173], v[202:205], v[114:117]
	v_mfma_f32_16x16x32_bf16 v[102:105], v[152:155], v[210:213], v[102:105]
	v_mfma_f32_16x16x32_bf16 v[98:101], v[170:173], v[210:213], v[98:101]
	v_mfma_f32_16x16x32_bf16 v[86:89], v[152:155], v[218:221], v[86:89]
	v_mfma_f32_16x16x32_bf16 v[82:85], v[170:173], v[218:221], v[82:85]
	v_mfma_f32_16x16x32_bf16 v[126:129], v[166:169], v[198:201], v[126:129]
	v_mfma_f32_16x16x32_bf16 v[122:125], v[174:177], v[198:201], v[122:125]
	v_mfma_f32_16x16x32_bf16 v[118:121], v[166:169], v[206:209], v[118:121]
	v_mfma_f32_16x16x32_bf16 v[114:117], v[174:177], v[206:209], v[114:117]
	v_mfma_f32_16x16x32_bf16 v[102:105], v[166:169], v[214:217], v[102:105]
	v_mfma_f32_16x16x32_bf16 v[98:101], v[174:177], v[214:217], v[98:101]
	v_mfma_f32_16x16x32_bf16 v[86:89], v[166:169], v[222:225], v[86:89]
	v_mfma_f32_16x16x32_bf16 v[82:85], v[174:177], v[222:225], v[82:85]
	s_setprio 0
	s_setprio 1
	v_mfma_f32_16x16x32_bf16 v[110:113], v[178:181], v[194:197], v[110:113]
	v_mfma_f32_16x16x32_bf16 v[106:109], v[186:189], v[194:197], v[106:109]
	v_mfma_f32_16x16x32_bf16 v[94:97], v[178:181], v[202:205], v[94:97]
	v_mfma_f32_16x16x32_bf16 v[90:93], v[186:189], v[202:205], v[90:93]
	v_mfma_f32_16x16x32_bf16 v[78:81], v[178:181], v[210:213], v[78:81]
	v_mfma_f32_16x16x32_bf16 v[74:77], v[186:189], v[210:213], v[74:77]
	v_mfma_f32_16x16x32_bf16 v[70:73], v[178:181], v[218:221], v[70:73]
	v_mfma_f32_16x16x32_bf16 v[66:69], v[186:189], v[218:221], v[66:69]
	v_mfma_f32_16x16x32_bf16 v[110:113], v[182:185], v[198:201], v[110:113]
	v_mfma_f32_16x16x32_bf16 v[106:109], v[190:193], v[198:201], v[106:109]
	v_mfma_f32_16x16x32_bf16 v[94:97], v[182:185], v[206:209], v[94:97]
	v_mfma_f32_16x16x32_bf16 v[90:93], v[190:193], v[206:209], v[90:93]
	v_mfma_f32_16x16x32_bf16 v[78:81], v[182:185], v[214:217], v[78:81]
	v_mfma_f32_16x16x32_bf16 v[74:77], v[190:193], v[214:217], v[74:77]
	v_mfma_f32_16x16x32_bf16 v[70:73], v[182:185], v[222:225], v[70:73]
	v_mfma_f32_16x16x32_bf16 v[66:69], v[190:193], v[222:225], v[66:69]
	s_setprio 0
	s_barrier
	s_add_i32 s33, s33, s25
	s_add_u32 s98, s54, 0x80
	s_addc_u32 s99, s55, 0
	s_mov_b32 m0, s33
	s_nop 0
	global_load_lds_dwordx4 v134, s[98:99]
	s_add_i32 m0, s33, 0x2000
	s_add_u32 s54, s54, 0x40080
	s_addc_u32 s55, s55, 0
	s_add_i32 s33, s80, s25
	global_load_lds_dwordx4 v130, s[98:99]
	s_mov_b32 m0, s33
	s_nop 0
	global_load_lds_dwordx4 v134, s[54:55]
	s_add_i32 m0, s33, 0x2000
	s_nop 0
	global_load_lds_dwordx4 v130, s[54:55]
	s_mov_b32 m0, s62
	s_nop 0
	global_load_lds_dwordx4 v136, s[100:101]
	s_mov_b32 m0, s63
	s_nop 0
	global_load_lds_dwordx4 v132, s[100:101]
	ds_read_b128 v[194:197], v165 offset:49152
	ds_read_b128 v[198:201], v165 offset:50176
	ds_read_b128 v[202:205], v165 offset:51200
	ds_read_b128 v[206:209], v165 offset:52224
	ds_read_b128 v[210:213], v165 offset:53248
	ds_read_b128 v[214:217], v165 offset:54272
	ds_read_b128 v[218:221], v165 offset:55296
	ds_read_b128 v[222:225], v165 offset:56320
	s_waitcnt vmcnt(8)
	s_waitcnt lgkmcnt(0)
	s_barrier
	s_setprio 1
	s_waitcnt lgkmcnt(0)
	v_mfma_f32_16x16x32_bf16 v[62:65], v[152:155], v[194:197], v[62:65]
	v_mfma_f32_16x16x32_bf16 v[58:61], v[170:173], v[194:197], v[58:61]
	v_mfma_f32_16x16x32_bf16 v[54:57], v[152:155], v[202:205], v[54:57]
	v_mfma_f32_16x16x32_bf16 v[50:53], v[170:173], v[202:205], v[50:53]
	v_mfma_f32_16x16x32_bf16 v[38:41], v[152:155], v[210:213], v[38:41]
	v_mfma_f32_16x16x32_bf16 v[34:37], v[170:173], v[210:213], v[34:37]
	v_mfma_f32_16x16x32_bf16 v[22:25], v[152:155], v[218:221], v[22:25]
	v_mfma_f32_16x16x32_bf16 v[18:21], v[170:173], v[218:221], v[18:21]
	v_mfma_f32_16x16x32_bf16 v[62:65], v[166:169], v[198:201], v[62:65]
	v_mfma_f32_16x16x32_bf16 v[58:61], v[174:177], v[198:201], v[58:61]
	v_mfma_f32_16x16x32_bf16 v[54:57], v[166:169], v[206:209], v[54:57]
	v_mfma_f32_16x16x32_bf16 v[50:53], v[174:177], v[206:209], v[50:53]
	v_mfma_f32_16x16x32_bf16 v[38:41], v[166:169], v[214:217], v[38:41]
	v_mfma_f32_16x16x32_bf16 v[34:37], v[174:177], v[214:217], v[34:37]
	v_mfma_f32_16x16x32_bf16 v[22:25], v[166:169], v[222:225], v[22:25]
	v_mfma_f32_16x16x32_bf16 v[18:21], v[174:177], v[222:225], v[18:21]
	s_setprio 0
	s_setprio 1
	v_mfma_f32_16x16x32_bf16 v[46:49], v[178:181], v[194:197], v[46:49]
	v_mfma_f32_16x16x32_bf16 v[42:45], v[186:189], v[194:197], v[42:45]
	v_mfma_f32_16x16x32_bf16 v[30:33], v[178:181], v[202:205], v[30:33]
	v_mfma_f32_16x16x32_bf16 v[26:29], v[186:189], v[202:205], v[26:29]
	v_mfma_f32_16x16x32_bf16 v[14:17], v[178:181], v[210:213], v[14:17]
	v_mfma_f32_16x16x32_bf16 v[10:13], v[186:189], v[210:213], v[10:13]
	v_mfma_f32_16x16x32_bf16 v[6:9], v[178:181], v[218:221], v[6:9]
	v_mfma_f32_16x16x32_bf16 v[2:5], v[186:189], v[218:221], v[2:5]
	v_mfma_f32_16x16x32_bf16 v[46:49], v[182:185], v[198:201], v[46:49]
	v_mfma_f32_16x16x32_bf16 v[42:45], v[190:193], v[198:201], v[42:45]
	v_mfma_f32_16x16x32_bf16 v[30:33], v[182:185], v[206:209], v[30:33]
	v_mfma_f32_16x16x32_bf16 v[26:29], v[190:193], v[206:209], v[26:29]
	v_mfma_f32_16x16x32_bf16 v[14:17], v[182:185], v[214:217], v[14:17]
	v_mfma_f32_16x16x32_bf16 v[10:13], v[190:193], v[214:217], v[10:13]
	v_mfma_f32_16x16x32_bf16 v[6:9], v[182:185], v[222:225], v[6:9]
	v_mfma_f32_16x16x32_bf16 v[2:5], v[190:193], v[222:225], v[2:5]
	s_setprio 0
	s_barrier
	s_add_i32 s92, s92, 2
	s_add_u32 s52, s52, 0x100
	s_addc_u32 s53, s53, 0
	s_add_u32 s90, s90, 0x100
	s_addc_u32 s91, s91, 0
	s_cmp_gt_u32 s92, 13
	s_cbranch_scc0 .LBB0_163
	s_and_b64 vcc, exec, s[14:15]
	s_cbranch_vccz .LBB0_166
	s_barrier

	.amdhsa_kernel _Z10hybrid_fwd6Params
		.amdhsa_group_segment_fixed_size 0
		.amdhsa_private_segment_fixed_size 0
		.amdhsa_kernarg_size 456
		.amdhsa_user_sgpr_count 2
		.amdhsa_user_sgpr_dispatch_ptr 0
		.amdhsa_user_sgpr_queue_ptr 0
		.amdhsa_user_sgpr_kernarg_segment_ptr 1
		.amdhsa_user_sgpr_dispatch_id 0
		.amdhsa_user_sgpr_kernarg_preload_length 0
		.amdhsa_user_sgpr_kernarg_preload_offset 0
		.amdhsa_user_sgpr_private_segment_size 0
		.amdhsa_uses_dynamic_stack 0
		.amdhsa_enable_private_segment 0
		.amdhsa_system_sgpr_workgroup_id_x 1
		.amdhsa_system_sgpr_workgroup_id_y 0
		.amdhsa_system_sgpr_workgroup_id_z 0
		.amdhsa_system_sgpr_workgroup_info 0
		.amdhsa_system_vgpr_workitem_id 2
		.amdhsa_next_free_vgpr 255
		.amdhsa_next_free_sgpr 102
		.amdhsa_accum_offset 256
		.amdhsa_reserve_vcc 1
		.amdhsa_float_round_mode_32 0
		.amdhsa_float_round_mode_16_64 0
		.amdhsa_float_denorm_mode_32 3
		.amdhsa_float_denorm_mode_16_64 3
		.amdhsa_dx10_clamp 1
		.amdhsa_ieee_mode 1
		.amdhsa_fp16_overflow 0
		.amdhsa_tg_split 0
		.amdhsa_exception_fp_ieee_invalid_op 0
		.amdhsa_exception_fp_denorm_src 0
		.amdhsa_exception_fp_ieee_div_zero 0
		.amdhsa_exception_fp_ieee_overflow 0
		.amdhsa_exception_fp_ieee_underflow 0
		.amdhsa_exception_fp_ieee_inexact 0
		.amdhsa_exception_int_div_zero 0
	.end_amdhsa_kernel

amdhsa.kernels:
  - .agpr_count:     0
    .args:
      - .offset:         0
        .size:           200
        .value_kind:     by_value
      - .offset:         200
        .size:           4
        .value_kind:     hidden_block_count_x
      - .offset:         204
        .size:           4
        .value_kind:     hidden_block_count_y
      - .offset:         208
        .size:           4
        .value_kind:     hidden_block_count_z
      - .offset:         212
        .size:           2
        .value_kind:     hidden_group_size_x
      - .offset:         214
        .size:           2
        .value_kind:     hidden_group_size_y
      - .offset:         216
        .size:           2
        .value_kind:     hidden_group_size_z
      - .offset:         218
        .size:           2
        .value_kind:     hidden_remainder_x
      - .offset:         220
        .size:           2
        .value_kind:     hidden_remainder_y
      - .offset:         222
        .size:           2
        .value_kind:     hidden_remainder_z
      - .offset:         240
        .size:           8
        .value_kind:     hidden_global_offset_x
      - .offset:         248
        .size:           8
        .value_kind:     hidden_global_offset_y
      - .offset:         256
        .size:           8
        .value_kind:     hidden_global_offset_z
      - .offset:         264
        .size:           2
        .value_kind:     hidden_grid_dims
      - .offset:         288
        .size:           8
        .value_kind:     hidden_multigrid_sync_arg
      - .offset:         320
        .size:           4
        .value_kind:     hidden_dynamic_lds_size
    .group_segment_fixed_size: 0
    .kernarg_segment_align: 8
    .kernarg_segment_size: 456
    .language:       OpenCL C
    .language_version:
      - 2
      - 0
    .max_flat_workgroup_size: 512
    .name:           _Z10hybrid_fwd6Params
    .private_segment_fixed_size: 0
    .sgpr_count:     108
    .sgpr_spill_count: 55
    .symbol:         _Z10hybrid_fwd6Params.kd
    .uniform_work_group_size: 1
    .uses_dynamic_stack: false
    .vgpr_count:     255
    .vgpr_spill_count: 0
    .wavefront_size: 64
